# grid barrier spin loops: poll back-off lengthened from s_sleep 1 to s_sleep 6 (less poller pressure on the leaders' flush and atomics)
# speedup vs baseline: 1.0233x; 1.0074x over previous
; __global__ void __launch_bounds__(512, 2) fwd_megakernel(Params P) {
;     ...
;     if (ws == nullptr) grid.sync();
.LBB0_11:
	s_sleep 6
	global_load_dword v3, v2, s[6:7] offset:32 sc1
	s_waitcnt vmcnt(0)
	v_and_b32_e32 v3, 0xffff0000, v3
	v_cmp_ne_u32_e32 vcc, v3, v1
	s_or_b64 s[8:9], vcc, s[8:9]
	s_andn2_b64 exec, exec, s[8:9]
	s_cbranch_execnz .LBB0_11

; __device__ __forceinline__ unsigned xb_ld(unsigned* p)              { return __hip_atomic_load(p, __ATOMIC_RELAXED, __HIP_MEMORY_SCOPE_AGENT); }
; __device__ __forceinline__ void xcd_barrier_complete(unsigned* bar, unsigned x, unsigned& nloc, unsigned& nx) {
;     ...
;     for (;;) {
;         sum = 0u; cnt = 0u; mine = 0u;
; #pragma unroll
;         for (unsigned j = 0; j < 16; ++j) { const unsigned c = xb_ld(&bar[XB_XCNT(j)]); sum += c; cnt += (c > 0u) ? 1u : 0u; mine = (j == x) ? c : mine; }
;         if (sum == G) break;
;         __builtin_amdgcn_s_sleep(1);
;         if ((++sp & 255u) == 0u) { if (xb_ld(&bar[XB_TMO])) break; if (sp > XB_SPIN_CAP) { atomicAdd(&bar[XB_TMO], 1u); break; } }
;     }
.LBB0_92:
	global_load_dword v16, v1, s[84:85] offset:1024 sc1
	global_load_dword v0, v1, s[84:85] offset:1280 sc1
	s_waitcnt lgkmcnt(0)
	global_load_dword v2, v1, s[84:85] offset:1536 sc1
	global_load_dword v3, v1, s[84:85] offset:1792 sc1
	global_load_dword v4, v1, s[84:85] offset:2048 sc1
	global_load_dword v5, v1, s[84:85] offset:2304 sc1
	global_load_dword v6, v1, s[84:85] offset:2560 sc1
	global_load_dword v7, v1, s[84:85] offset:2816 sc1
	global_load_dword v8, v1, s[84:85] offset:3072 sc1
	global_load_dword v9, v1, s[84:85] offset:3328 sc1
	global_load_dword v10, v1, s[84:85] offset:3584 sc1
	global_load_dword v11, v1, s[84:85] offset:3840 sc1
	global_load_dword v12, v1, s[48:49] sc1
	global_load_dword v13, v1, s[50:51] sc1
	global_load_dword v14, v1, s[52:53] sc1
	global_load_dword v15, v1, s[54:55] sc1
	s_mov_b64 s[10:11], -1
	s_mov_b64 s[14:15], -1
	s_waitcnt vmcnt(14)
	v_add_u32_e32 v17, v0, v16
	s_waitcnt vmcnt(13)
	v_add_u32_e32 v17, v17, v2
	s_waitcnt vmcnt(12)
	v_add_u32_e32 v17, v17, v3
	s_waitcnt vmcnt(11)
	v_add_u32_e32 v17, v17, v4
	s_waitcnt vmcnt(10)
	v_add_u32_e32 v17, v17, v5
	s_waitcnt vmcnt(9)
	v_add_u32_e32 v17, v17, v6
	s_waitcnt vmcnt(8)
	v_add_u32_e32 v17, v17, v7
	s_waitcnt vmcnt(7)
	v_add_u32_e32 v17, v17, v8
	s_waitcnt vmcnt(6)
	v_add_u32_e32 v17, v17, v9
	s_waitcnt vmcnt(5)
	v_add_u32_e32 v17, v17, v10
	s_waitcnt vmcnt(4)
	v_add_u32_e32 v17, v17, v11
	s_waitcnt vmcnt(3)
	v_add_u32_e32 v17, v17, v12
	s_waitcnt vmcnt(2)
	v_add_u32_e32 v17, v17, v13
	s_waitcnt vmcnt(1)
	v_add_u32_e32 v17, v17, v14
	s_waitcnt vmcnt(0)
	v_add_u32_e32 v17, v17, v15
	v_cmp_eq_u32_e32 vcc, s39, v17
	s_cbranch_vccnz .LBB0_91
	s_and_b32 s5, s4, 0xff
	s_cmp_eq_u32 s5, 0
	s_mov_b64 s[16:17], -1
	s_sleep 6
	s_cbranch_scc0 .LBB0_96
	global_load_dword v17, v1, s[82:83] sc1
	s_waitcnt vmcnt(0)
	v_cmp_eq_u32_e32 vcc, 0, v17
	s_cbranch_vccnz .LBB0_98
	s_mov_b64 s[16:17], 0

.LBB0_110:
	s_and_b32 s5, s4, 0xff
	s_mov_b64 s[22:23], -1
	s_cmp_lg_u32 s5, 0
	s_mov_b64 s[24:25], -1
	s_sleep 6
	s_cbranch_scc1 .LBB0_113
	global_load_dword v2, v1, s[82:83] sc1
	s_waitcnt vmcnt(0)
	v_cmp_eq_u32_e32 vcc, 0, v2
	s_cbranch_vccnz .LBB0_115
	s_mov_b64 s[24:25], 0
	s_mov_b64 s[38:39], -1
